# chain dma+stores plus gla_prep gate projections as v_pk_fma_f32 chains (same f32 FMAs, same order; 32 -> 19 VALU per row)
# baseline (speedup 1.0000x reference)
; #define LAS __attribute__((address_space(3)))
; DI float logsigmoid_fast(float z) { return fminf(z, 0.f) - 0.6931471805599453f * __builtin_amdgcn_logf(1.0f + __builtin_amdgcn_exp2f(-fabsf(z) * LOG2E)); }
; DI void phase_gla_prep(const Params& P, int l, int bid, int nb, LAS unsigned char* lds) {
;     ...
;             float w0[16], w1[16];
; #pragma unroll
;             for (int k = 0; k < 16; ++k) { const f32x2 t = *(const LAS f32x2*)(lds + PP_W + ((dir * 16 + k) * 128 + c0) * 4); w0[k] = t.x; w1[k] = t.y; }
;             const f32x2 bb = dir ? bbs[1] : bbs[0];
;             float g0[8], g1[8];
; #pragma unroll
;             for (int r = 0; r < 8; ++r) { float z0 = bb.x, z1 = bb.y; const LAS float* lr = (const LAS float*)(lds + PP_LR) + (rg * 8 + r) * 32 + dir * 16;
; #pragma unroll
;                 for (int k4 = 0; k4 < 4; ++k4) { const f32x4 t = *(const LAS f32x4*)(lr + k4 * 4);
; #pragma unroll
;                     for (int u = 0; u < 4; ++u) { z0 += t[u] * w0[k4 * 4 + u]; z1 += t[u] * w1[k4 * 4 + u]; } }
;                 g0[r] = logsigmoid_fast(z0) * 0.0625f; g1[r] = logsigmoid_fast(z1) * 0.0625f; __builtin_amdgcn_sched_barrier(0); }
.LBB0_344:
	s_lshl_b32 s90, s76, 13
	v_add_u32_e32 v2, s90, v142
	v_add_u32_e32 v3, s90, v143
	v_add_u32_e32 v4, s90, v144
	v_add_u32_e32 v5, s90, v145
	ds_read_b64 v[134:135], v2
	ds_read_b64 v[132:133], v3
	ds_read_b64 v[128:129], v4
	ds_read_b64 v[124:125], v5
	v_add_u32_e32 v2, s90, v146
	v_add_u32_e32 v3, s90, v147
	v_add_u32_e32 v4, s90, v148
	v_add_u32_e32 v5, s90, v149
	ds_read_b64 v[130:131], v2
	ds_read_b64 v[126:127], v3
	ds_read_b64 v[120:121], v4
	ds_read_b64 v[14:15], v5
	v_add_u32_e32 v2, s90, v150
	v_add_u32_e32 v3, s90, v151
	v_add_u32_e32 v4, s90, v152
	v_add_u32_e32 v5, s90, v153
	ds_read_b64 v[122:123], v2
	ds_read_b64 v[16:17], v3
	ds_read_b64 v[10:11], v4
	ds_read_b64 v[6:7], v5
	v_add_u32_e32 v2, s90, v154
	v_add_u32_e32 v3, s90, v155
	v_add_u32_e32 v4, s90, v156
	v_lshl_add_u32 v223, s76, 6, v175
	v_add_u32_e32 v116, s90, v157
	ds_read_b64 v[12:13], v2
	ds_read_b64 v[8:9], v3
	ds_read_b64 v[4:5], v4
	ds_read_b64 v[2:3], v116
	ds_read_b128 v[224:227], v223
	v_cndmask_b32_e64 v119, v82, v80, s[88:89]
	v_cndmask_b32_e64 v117, v83, v81, s[88:89]
	ds_read_b128 v[228:231], v223 offset:16
	ds_read_b128 v[232:235], v223 offset:32
	ds_read_b128 v[236:239], v223 offset:48
	s_waitcnt lgkmcnt(0)
	v_fma_f32 v240, v134, v224, v119
	v_fma_f32 v241, v135, v224, v117
	v_pk_fma_f32 v[240:241], v[132:133], v[224:225], v[240:241] op_sel:[0,1,0] op_sel_hi:[1,1,1]
	v_pk_fma_f32 v[240:241], v[128:129], v[226:227], v[240:241] op_sel:[0,0,0] op_sel_hi:[1,0,1]
	v_pk_fma_f32 v[240:241], v[124:125], v[226:227], v[240:241] op_sel:[0,1,0] op_sel_hi:[1,1,1]
	v_pk_fma_f32 v[240:241], v[130:131], v[228:229], v[240:241] op_sel:[0,0,0] op_sel_hi:[1,0,1]
	v_pk_fma_f32 v[240:241], v[126:127], v[228:229], v[240:241] op_sel:[0,1,0] op_sel_hi:[1,1,1]
	v_pk_fma_f32 v[240:241], v[120:121], v[230:231], v[240:241] op_sel:[0,0,0] op_sel_hi:[1,0,1]
	v_pk_fma_f32 v[240:241], v[14:15], v[230:231], v[240:241] op_sel:[0,1,0] op_sel_hi:[1,1,1]
	v_pk_fma_f32 v[240:241], v[122:123], v[232:233], v[240:241] op_sel:[0,0,0] op_sel_hi:[1,0,1]
	v_pk_fma_f32 v[240:241], v[16:17], v[232:233], v[240:241] op_sel:[0,1,0] op_sel_hi:[1,1,1]
	v_pk_fma_f32 v[240:241], v[10:11], v[234:235], v[240:241] op_sel:[0,0,0] op_sel_hi:[1,0,1]
	v_pk_fma_f32 v[240:241], v[6:7], v[234:235], v[240:241] op_sel:[0,1,0] op_sel_hi:[1,1,1]
	v_pk_fma_f32 v[240:241], v[12:13], v[236:237], v[240:241] op_sel:[0,0,0] op_sel_hi:[1,0,1]
	v_pk_fma_f32 v[240:241], v[8:9], v[236:237], v[240:241] op_sel:[0,1,0] op_sel_hi:[1,1,1]
	v_pk_fma_f32 v[240:241], v[4:5], v[238:239], v[240:241] op_sel:[0,0,0] op_sel_hi:[1,0,1]
	v_fma_f32 v116, v2, v239, v240
	v_fma_f32 v221, v3, v239, v241
	v_mul_f32_e64 v118, |v116|, s96
	v_exp_f32_e32 v118, v118
	v_mul_f32_e64 v222, |v221|, s96
	v_exp_f32_e32 v222, v222
	v_add_f32_e32 v118, 1.0, v118
	v_log_f32_e32 v118, v118
	v_min_f32_e32 v116, 0, v116
	v_add_f32_e32 v222, 1.0, v222
	v_log_f32_e32 v222, v222
	v_fmac_f32_e32 v116, 0xbf317218, v118
	v_mul_f32_e32 v118, 0x3d800000, v116
	v_min_f32_e32 v116, 0, v221
	v_fmac_f32_e32 v116, 0xbf317218, v222
	v_mul_f32_e32 v116, 0x3d800000, v116
	ds_read_b128 v[224:227], v223 offset:128
	ds_read_b128 v[228:231], v223 offset:144
	ds_read_b128 v[232:235], v223 offset:160
	ds_read_b128 v[236:239], v223 offset:176
	s_waitcnt lgkmcnt(3)
	v_fma_f32 v240, v134, v224, v119
	v_fma_f32 v241, v135, v224, v117
	v_pk_fma_f32 v[240:241], v[132:133], v[224:225], v[240:241] op_sel:[0,1,0] op_sel_hi:[1,1,1]
	v_pk_fma_f32 v[240:241], v[128:129], v[226:227], v[240:241] op_sel:[0,0,0] op_sel_hi:[1,0,1]
	v_pk_fma_f32 v[240:241], v[124:125], v[226:227], v[240:241] op_sel:[0,1,0] op_sel_hi:[1,1,1]
	s_waitcnt lgkmcnt(2)
	v_pk_fma_f32 v[240:241], v[130:131], v[228:229], v[240:241] op_sel:[0,0,0] op_sel_hi:[1,0,1]
	v_pk_fma_f32 v[240:241], v[126:127], v[228:229], v[240:241] op_sel:[0,1,0] op_sel_hi:[1,1,1]
	v_pk_fma_f32 v[240:241], v[120:121], v[230:231], v[240:241] op_sel:[0,0,0] op_sel_hi:[1,0,1]
	v_pk_fma_f32 v[240:241], v[14:15], v[230:231], v[240:241] op_sel:[0,1,0] op_sel_hi:[1,1,1]
	s_waitcnt lgkmcnt(1)
	v_pk_fma_f32 v[240:241], v[122:123], v[232:233], v[240:241] op_sel:[0,0,0] op_sel_hi:[1,0,1]
	v_pk_fma_f32 v[240:241], v[16:17], v[232:233], v[240:241] op_sel:[0,1,0] op_sel_hi:[1,1,1]
	v_pk_fma_f32 v[240:241], v[10:11], v[234:235], v[240:241] op_sel:[0,0,0] op_sel_hi:[1,0,1]
	v_pk_fma_f32 v[240:241], v[6:7], v[234:235], v[240:241] op_sel:[0,1,0] op_sel_hi:[1,1,1]
	s_waitcnt lgkmcnt(0)
	v_pk_fma_f32 v[240:241], v[12:13], v[236:237], v[240:241] op_sel:[0,0,0] op_sel_hi:[1,0,1]
	v_pk_fma_f32 v[240:241], v[8:9], v[236:237], v[240:241] op_sel:[0,1,0] op_sel_hi:[1,1,1]
	v_pk_fma_f32 v[240:241], v[4:5], v[238:239], v[240:241] op_sel:[0,0,0] op_sel_hi:[1,0,1]
	v_fma_f32 v221, v2, v239, v240
	v_fma_f32 v222, v3, v239, v241
	v_mul_f32_e64 v224, |v221|, s96
	v_mul_f32_e64 v225, |v222|, s96
	v_exp_f32_e32 v224, v224
	v_exp_f32_e32 v225, v225
	v_min_f32_e32 v221, 0, v221
	v_min_f32_e32 v222, 0, v222
	v_add_f32_e32 v224, 1.0, v224
	v_add_f32_e32 v225, 1.0, v225
	v_log_f32_e32 v224, v224
	v_log_f32_e32 v225, v225
	v_fmac_f32_e32 v221, 0xbf317218, v224
	v_fmac_f32_e32 v222, 0xbf317218, v225
	v_mul_f32_e32 v221, 0x3d800000, v221
	v_mul_f32_e32 v222, 0x3d800000, v222
	ds_read_b128 v[224:227], v223 offset:256
	ds_read_b128 v[228:231], v223 offset:272
	ds_read_b128 v[232:235], v223 offset:288
	ds_read_b128 v[236:239], v223 offset:304
	s_waitcnt lgkmcnt(3)
	v_fma_f32 v242, v134, v224, v119
	v_fma_f32 v243, v135, v224, v117
	v_pk_fma_f32 v[242:243], v[132:133], v[224:225], v[242:243] op_sel:[0,1,0] op_sel_hi:[1,1,1]
	v_pk_fma_f32 v[242:243], v[128:129], v[226:227], v[242:243] op_sel:[0,0,0] op_sel_hi:[1,0,1]
	v_pk_fma_f32 v[242:243], v[124:125], v[226:227], v[242:243] op_sel:[0,1,0] op_sel_hi:[1,1,1]
	s_waitcnt lgkmcnt(2)
; #define LAS __attribute__((address_space(3)))
; DI float logsigmoid_fast(float z) { return fminf(z, 0.f) - 0.6931471805599453f * __builtin_amdgcn_logf(1.0f + __builtin_amdgcn_exp2f(-fabsf(z) * LOG2E)); }
; DI void phase_gla_prep(const Params& P, int l, int bid, int nb, LAS unsigned char* lds) {
;     ...
;             float w0[16], w1[16];
; #pragma unroll
;             for (int k = 0; k < 16; ++k) { const f32x2 t = *(const LAS f32x2*)(lds + PP_W + ((dir * 16 + k) * 128 + c0) * 4); w0[k] = t.x; w1[k] = t.y; }
;             const f32x2 bb = dir ? bbs[1] : bbs[0];
;             float g0[8], g1[8];
; #pragma unroll
;             for (int r = 0; r < 8; ++r) { float z0 = bb.x, z1 = bb.y; const LAS float* lr = (const LAS float*)(lds + PP_LR) + (rg * 8 + r) * 32 + dir * 16;
; #pragma unroll
;                 for (int k4 = 0; k4 < 4; ++k4) { const f32x4 t = *(const LAS f32x4*)(lr + k4 * 4);
; #pragma unroll
;                     for (int u = 0; u < 4; ++u) { z0 += t[u] * w0[k4 * 4 + u]; z1 += t[u] * w1[k4 * 4 + u]; } }
;                 g0[r] = logsigmoid_fast(z0) * 0.0625f; g1[r] = logsigmoid_fast(z1) * 0.0625f; __builtin_amdgcn_sched_barrier(0); }
	v_pk_fma_f32 v[242:243], v[130:131], v[228:229], v[242:243] op_sel:[0,0,0] op_sel_hi:[1,0,1]
	v_pk_fma_f32 v[242:243], v[126:127], v[228:229], v[242:243] op_sel:[0,1,0] op_sel_hi:[1,1,1]
	v_pk_fma_f32 v[242:243], v[120:121], v[230:231], v[242:243] op_sel:[0,0,0] op_sel_hi:[1,0,1]
	v_pk_fma_f32 v[242:243], v[14:15], v[230:231], v[242:243] op_sel:[0,1,0] op_sel_hi:[1,1,1]
	s_waitcnt lgkmcnt(1)
	v_pk_fma_f32 v[242:243], v[122:123], v[232:233], v[242:243] op_sel:[0,0,0] op_sel_hi:[1,0,1]
	v_pk_fma_f32 v[242:243], v[16:17], v[232:233], v[242:243] op_sel:[0,1,0] op_sel_hi:[1,1,1]
	v_pk_fma_f32 v[242:243], v[10:11], v[234:235], v[242:243] op_sel:[0,0,0] op_sel_hi:[1,0,1]
	v_pk_fma_f32 v[242:243], v[6:7], v[234:235], v[242:243] op_sel:[0,1,0] op_sel_hi:[1,1,1]
	s_waitcnt lgkmcnt(0)
	v_pk_fma_f32 v[242:243], v[12:13], v[236:237], v[242:243] op_sel:[0,0,0] op_sel_hi:[1,0,1]
	v_pk_fma_f32 v[242:243], v[8:9], v[236:237], v[242:243] op_sel:[0,1,0] op_sel_hi:[1,1,1]
	v_pk_fma_f32 v[242:243], v[4:5], v[238:239], v[242:243] op_sel:[0,0,0] op_sel_hi:[1,0,1]
	v_fma_f32 v240, v2, v239, v242
	v_fma_f32 v224, v3, v239, v243
	v_mul_f32_e64 v225, |v240|, s96
	v_mul_f32_e64 v226, |v224|, s96
	v_exp_f32_e32 v225, v225
	v_exp_f32_e32 v226, v226
	v_min_f32_e32 v227, 0, v240
	v_min_f32_e32 v224, 0, v224
	v_add_f32_e32 v225, 1.0, v225
	v_add_f32_e32 v226, 1.0, v226
	v_log_f32_e32 v225, v225
	v_log_f32_e32 v226, v226
	v_fmac_f32_e32 v227, 0xbf317218, v225
	v_fmac_f32_e32 v224, 0xbf317218, v226
	v_mul_f32_e32 v225, 0x3d800000, v227
	v_mul_f32_e32 v224, 0x3d800000, v224
	ds_read_b128 v[226:229], v223 offset:384
	ds_read_b128 v[230:233], v223 offset:400
	ds_read_b128 v[234:237], v223 offset:416
	ds_read_b128 v[238:241], v223 offset:432
	s_waitcnt lgkmcnt(3)
	v_fma_f32 v244, v134, v226, v119
	v_fma_f32 v245, v135, v226, v117
	v_pk_fma_f32 v[244:245], v[132:133], v[226:227], v[244:245] op_sel:[0,1,0] op_sel_hi:[1,1,1]
	v_pk_fma_f32 v[244:245], v[128:129], v[228:229], v[244:245] op_sel:[0,0,0] op_sel_hi:[1,0,1]
	v_pk_fma_f32 v[244:245], v[124:125], v[228:229], v[244:245] op_sel:[0,1,0] op_sel_hi:[1,1,1]
	s_waitcnt lgkmcnt(2)
	v_pk_fma_f32 v[244:245], v[130:131], v[230:231], v[244:245] op_sel:[0,0,0] op_sel_hi:[1,0,1]
	v_pk_fma_f32 v[244:245], v[126:127], v[230:231], v[244:245] op_sel:[0,1,0] op_sel_hi:[1,1,1]
	v_pk_fma_f32 v[244:245], v[120:121], v[232:233], v[244:245] op_sel:[0,0,0] op_sel_hi:[1,0,1]
	v_pk_fma_f32 v[244:245], v[14:15], v[232:233], v[244:245] op_sel:[0,1,0] op_sel_hi:[1,1,1]
	s_waitcnt lgkmcnt(1)
	v_pk_fma_f32 v[244:245], v[122:123], v[234:235], v[244:245] op_sel:[0,0,0] op_sel_hi:[1,0,1]
	v_pk_fma_f32 v[244:245], v[16:17], v[234:235], v[244:245] op_sel:[0,1,0] op_sel_hi:[1,1,1]
	v_pk_fma_f32 v[244:245], v[10:11], v[236:237], v[244:245] op_sel:[0,0,0] op_sel_hi:[1,0,1]
	v_pk_fma_f32 v[244:245], v[6:7], v[236:237], v[244:245] op_sel:[0,1,0] op_sel_hi:[1,1,1]
	s_waitcnt lgkmcnt(0)
	v_pk_fma_f32 v[244:245], v[12:13], v[238:239], v[244:245] op_sel:[0,0,0] op_sel_hi:[1,0,1]
	v_pk_fma_f32 v[244:245], v[8:9], v[238:239], v[244:245] op_sel:[0,1,0] op_sel_hi:[1,1,1]
	v_pk_fma_f32 v[244:245], v[4:5], v[240:241], v[244:245] op_sel:[0,0,0] op_sel_hi:[1,0,1]
	v_fma_f32 v242, v2, v241, v244
	v_fma_f32 v226, v3, v241, v245
	v_mul_f32_e64 v227, |v242|, s96
	v_mul_f32_e64 v228, |v226|, s96
	v_exp_f32_e32 v227, v227
	v_exp_f32_e32 v228, v228
	v_min_f32_e32 v229, 0, v242
	v_min_f32_e32 v226, 0, v226
	v_add_f32_e32 v227, 1.0, v227
	v_add_f32_e32 v228, 1.0, v228
	v_log_f32_e32 v227, v227
	v_log_f32_e32 v228, v228
	v_fmac_f32_e32 v229, 0xbf317218, v227
	v_fmac_f32_e32 v226, 0xbf317218, v228
	v_mul_f32_e32 v227, 0x3d800000, v229
	v_mul_f32_e32 v226, 0x3d800000, v226
	ds_read_b128 v[228:231], v223 offset:512
	ds_read_b128 v[232:235], v223 offset:528
	ds_read_b128 v[236:239], v223 offset:544
	ds_read_b128 v[240:243], v223 offset:560
	s_waitcnt lgkmcnt(3)
	v_fma_f32 v246, v134, v228, v119
	v_fma_f32 v247, v135, v228, v117
	v_pk_fma_f32 v[246:247], v[132:133], v[228:229], v[246:247] op_sel:[0,1,0] op_sel_hi:[1,1,1]
	v_pk_fma_f32 v[246:247], v[128:129], v[230:231], v[246:247] op_sel:[0,0,0] op_sel_hi:[1,0,1]
	v_pk_fma_f32 v[246:247], v[124:125], v[230:231], v[246:247] op_sel:[0,1,0] op_sel_hi:[1,1,1]
	s_waitcnt lgkmcnt(2)
	v_pk_fma_f32 v[246:247], v[130:131], v[232:233], v[246:247] op_sel:[0,0,0] op_sel_hi:[1,0,1]
	v_pk_fma_f32 v[246:247], v[126:127], v[232:233], v[246:247] op_sel:[0,1,0] op_sel_hi:[1,1,1]
	v_pk_fma_f32 v[246:247], v[120:121], v[234:235], v[246:247] op_sel:[0,0,0] op_sel_hi:[1,0,1]
	v_pk_fma_f32 v[246:247], v[14:15], v[234:235], v[246:247] op_sel:[0,1,0] op_sel_hi:[1,1,1]
	s_waitcnt lgkmcnt(1)
	v_pk_fma_f32 v[246:247], v[122:123], v[236:237], v[246:247] op_sel:[0,0,0] op_sel_hi:[1,0,1]
	v_pk_fma_f32 v[246:247], v[16:17], v[236:237], v[246:247] op_sel:[0,1,0] op_sel_hi:[1,1,1]
	v_pk_fma_f32 v[246:247], v[10:11], v[238:239], v[246:247] op_sel:[0,0,0] op_sel_hi:[1,0,1]
	v_pk_fma_f32 v[246:247], v[6:7], v[238:239], v[246:247] op_sel:[0,1,0] op_sel_hi:[1,1,1]
	s_waitcnt lgkmcnt(0)
	v_pk_fma_f32 v[246:247], v[12:13], v[240:241], v[246:247] op_sel:[0,0,0] op_sel_hi:[1,0,1]
	v_pk_fma_f32 v[246:247], v[8:9], v[240:241], v[246:247] op_sel:[0,1,0] op_sel_hi:[1,1,1]
	v_pk_fma_f32 v[246:247], v[4:5], v[242:243], v[246:247] op_sel:[0,0,0] op_sel_hi:[1,0,1]
	v_fma_f32 v244, v2, v243, v246
	v_fma_f32 v228, v3, v243, v247
	v_mul_f32_e64 v229, |v244|, s96
	v_mul_f32_e64 v230, |v228|, s96
	v_exp_f32_e32 v229, v229
	v_exp_f32_e32 v230, v230
	v_min_f32_e32 v231, 0, v244
	v_min_f32_e32 v228, 0, v228
	v_add_f32_e32 v229, 1.0, v229
	v_add_f32_e32 v230, 1.0, v230
	v_log_f32_e32 v229, v229
	v_log_f32_e32 v230, v230
	v_fmac_f32_e32 v231, 0xbf317218, v229
	v_fmac_f32_e32 v228, 0xbf317218, v230
	v_mul_f32_e32 v229, 0x3d800000, v231
	v_mul_f32_e32 v228, 0x3d800000, v228
	ds_read_b128 v[230:233], v223 offset:640
	ds_read_b128 v[234:237], v223 offset:656
	ds_read_b128 v[238:241], v223 offset:672
	ds_read_b128 v[242:245], v223 offset:688
	s_waitcnt lgkmcnt(3)
; #define LAS __attribute__((address_space(3)))
; DI float logsigmoid_fast(float z) { return fminf(z, 0.f) - 0.6931471805599453f * __builtin_amdgcn_logf(1.0f + __builtin_amdgcn_exp2f(-fabsf(z) * LOG2E)); }
; DI void phase_gla_prep(const Params& P, int l, int bid, int nb, LAS unsigned char* lds) {
;     ...
;             for (int r = 0; r < 8; ++r) { float z0 = bb.x, z1 = bb.y; const LAS float* lr = (const LAS float*)(lds + PP_LR) + (rg * 8 + r) * 32 + dir * 16;
; #pragma unroll
;                 for (int k4 = 0; k4 < 4; ++k4) { const f32x4 t = *(const LAS f32x4*)(lr + k4 * 4);
; #pragma unroll
;                     for (int u = 0; u < 4; ++u) { z0 += t[u] * w0[k4 * 4 + u]; z1 += t[u] * w1[k4 * 4 + u]; } }
;                 g0[r] = logsigmoid_fast(z0) * 0.0625f; g1[r] = logsigmoid_fast(z1) * 0.0625f; __builtin_amdgcn_sched_barrier(0); }
	v_fma_f32 v248, v134, v230, v119
	v_fma_f32 v249, v135, v230, v117
	v_pk_fma_f32 v[248:249], v[132:133], v[230:231], v[248:249] op_sel:[0,1,0] op_sel_hi:[1,1,1]
	v_pk_fma_f32 v[248:249], v[128:129], v[232:233], v[248:249] op_sel:[0,0,0] op_sel_hi:[1,0,1]
	v_pk_fma_f32 v[248:249], v[124:125], v[232:233], v[248:249] op_sel:[0,1,0] op_sel_hi:[1,1,1]
	s_waitcnt lgkmcnt(2)
	v_pk_fma_f32 v[248:249], v[130:131], v[234:235], v[248:249] op_sel:[0,0,0] op_sel_hi:[1,0,1]
	v_pk_fma_f32 v[248:249], v[126:127], v[234:235], v[248:249] op_sel:[0,1,0] op_sel_hi:[1,1,1]
	v_pk_fma_f32 v[248:249], v[120:121], v[236:237], v[248:249] op_sel:[0,0,0] op_sel_hi:[1,0,1]
	v_pk_fma_f32 v[248:249], v[14:15], v[236:237], v[248:249] op_sel:[0,1,0] op_sel_hi:[1,1,1]
	s_waitcnt lgkmcnt(1)
	v_pk_fma_f32 v[248:249], v[122:123], v[238:239], v[248:249] op_sel:[0,0,0] op_sel_hi:[1,0,1]
	v_pk_fma_f32 v[248:249], v[16:17], v[238:239], v[248:249] op_sel:[0,1,0] op_sel_hi:[1,1,1]
	v_pk_fma_f32 v[248:249], v[10:11], v[240:241], v[248:249] op_sel:[0,0,0] op_sel_hi:[1,0,1]
	v_pk_fma_f32 v[248:249], v[6:7], v[240:241], v[248:249] op_sel:[0,1,0] op_sel_hi:[1,1,1]
	s_waitcnt lgkmcnt(0)
	v_pk_fma_f32 v[248:249], v[12:13], v[242:243], v[248:249] op_sel:[0,0,0] op_sel_hi:[1,0,1]
	v_pk_fma_f32 v[248:249], v[8:9], v[242:243], v[248:249] op_sel:[0,1,0] op_sel_hi:[1,1,1]
	v_pk_fma_f32 v[248:249], v[4:5], v[244:245], v[248:249] op_sel:[0,0,0] op_sel_hi:[1,0,1]
	v_fma_f32 v246, v2, v245, v248
	v_fma_f32 v230, v3, v245, v249
	v_mul_f32_e64 v231, |v246|, s96
	v_mul_f32_e64 v232, |v230|, s96
	v_exp_f32_e32 v231, v231
	v_exp_f32_e32 v232, v232
	v_min_f32_e32 v233, 0, v246
	v_min_f32_e32 v230, 0, v230
	v_add_f32_e32 v231, 1.0, v231
	v_add_f32_e32 v232, 1.0, v232
	v_log_f32_e32 v231, v231
	v_log_f32_e32 v232, v232
	v_fmac_f32_e32 v233, 0xbf317218, v231
	v_fmac_f32_e32 v230, 0xbf317218, v232
	v_mul_f32_e32 v231, 0x3d800000, v233
	v_mul_f32_e32 v230, 0x3d800000, v230
	ds_read_b128 v[232:235], v223 offset:768
	ds_read_b128 v[236:239], v223 offset:784
	ds_read_b128 v[240:243], v223 offset:800
	ds_read_b128 v[244:247], v223 offset:816
	s_waitcnt lgkmcnt(3)
	v_fma_f32 v250, v134, v232, v119
	v_fma_f32 v251, v135, v232, v117
	v_pk_fma_f32 v[250:251], v[132:133], v[232:233], v[250:251] op_sel:[0,1,0] op_sel_hi:[1,1,1]
	v_pk_fma_f32 v[250:251], v[128:129], v[234:235], v[250:251] op_sel:[0,0,0] op_sel_hi:[1,0,1]
	v_pk_fma_f32 v[250:251], v[124:125], v[234:235], v[250:251] op_sel:[0,1,0] op_sel_hi:[1,1,1]
	s_waitcnt lgkmcnt(2)
	v_pk_fma_f32 v[250:251], v[130:131], v[236:237], v[250:251] op_sel:[0,0,0] op_sel_hi:[1,0,1]
	v_pk_fma_f32 v[250:251], v[126:127], v[236:237], v[250:251] op_sel:[0,1,0] op_sel_hi:[1,1,1]
	v_pk_fma_f32 v[250:251], v[120:121], v[238:239], v[250:251] op_sel:[0,0,0] op_sel_hi:[1,0,1]
	v_pk_fma_f32 v[250:251], v[14:15], v[238:239], v[250:251] op_sel:[0,1,0] op_sel_hi:[1,1,1]
	s_waitcnt lgkmcnt(1)
	v_pk_fma_f32 v[250:251], v[122:123], v[240:241], v[250:251] op_sel:[0,0,0] op_sel_hi:[1,0,1]
	v_pk_fma_f32 v[250:251], v[16:17], v[240:241], v[250:251] op_sel:[0,1,0] op_sel_hi:[1,1,1]
	v_pk_fma_f32 v[250:251], v[10:11], v[242:243], v[250:251] op_sel:[0,0,0] op_sel_hi:[1,0,1]
	v_pk_fma_f32 v[250:251], v[6:7], v[242:243], v[250:251] op_sel:[0,1,0] op_sel_hi:[1,1,1]
	s_waitcnt lgkmcnt(0)
	v_pk_fma_f32 v[250:251], v[12:13], v[244:245], v[250:251] op_sel:[0,0,0] op_sel_hi:[1,0,1]
	v_pk_fma_f32 v[250:251], v[8:9], v[244:245], v[250:251] op_sel:[0,1,0] op_sel_hi:[1,1,1]
	v_pk_fma_f32 v[250:251], v[4:5], v[246:247], v[250:251] op_sel:[0,0,0] op_sel_hi:[1,0,1]
	v_fma_f32 v248, v2, v247, v250
	v_fma_f32 v232, v3, v247, v251
	v_mul_f32_e64 v233, |v248|, s96
	v_mul_f32_e64 v234, |v232|, s96
	v_exp_f32_e32 v233, v233
	v_exp_f32_e32 v234, v234
	v_min_f32_e32 v235, 0, v248
	v_min_f32_e32 v232, 0, v232
	v_add_f32_e32 v233, 1.0, v233
	v_add_f32_e32 v234, 1.0, v234
	v_log_f32_e32 v233, v233
	v_log_f32_e32 v234, v234
	v_fmac_f32_e32 v235, 0xbf317218, v233
	v_fmac_f32_e32 v232, 0xbf317218, v234
	v_mul_f32_e32 v233, 0x3d800000, v235
	v_mul_f32_e32 v232, 0x3d800000, v232
	ds_read_b128 v[234:237], v223 offset:896
	ds_read_b128 v[238:241], v223 offset:912
	ds_read_b128 v[242:245], v223 offset:928
	ds_read_b128 v[246:249], v223 offset:944
	s_waitcnt lgkmcnt(3)
	v_fma_f32 v250, v134, v234, v119
	v_fma_f32 v251, v135, v234, v117
	v_pk_fma_f32 v[250:251], v[132:133], v[234:235], v[250:251] op_sel:[0,1,0] op_sel_hi:[1,1,1]
	v_pk_fma_f32 v[250:251], v[128:129], v[236:237], v[250:251] op_sel:[0,0,0] op_sel_hi:[1,0,1]
	v_pk_fma_f32 v[250:251], v[124:125], v[236:237], v[250:251] op_sel:[0,1,0] op_sel_hi:[1,1,1]
	s_waitcnt lgkmcnt(2)
	v_pk_fma_f32 v[250:251], v[130:131], v[238:239], v[250:251] op_sel:[0,0,0] op_sel_hi:[1,0,1]
	v_pk_fma_f32 v[250:251], v[126:127], v[238:239], v[250:251] op_sel:[0,1,0] op_sel_hi:[1,1,1]
	v_pk_fma_f32 v[250:251], v[120:121], v[240:241], v[250:251] op_sel:[0,0,0] op_sel_hi:[1,0,1]
	v_pk_fma_f32 v[250:251], v[14:15], v[240:241], v[250:251] op_sel:[0,1,0] op_sel_hi:[1,1,1]
	s_waitcnt lgkmcnt(1)
	v_pk_fma_f32 v[250:251], v[122:123], v[242:243], v[250:251] op_sel:[0,0,0] op_sel_hi:[1,0,1]
	v_pk_fma_f32 v[250:251], v[16:17], v[242:243], v[250:251] op_sel:[0,1,0] op_sel_hi:[1,1,1]
	v_pk_fma_f32 v[250:251], v[10:11], v[244:245], v[250:251] op_sel:[0,0,0] op_sel_hi:[1,0,1]
	v_pk_fma_f32 v[250:251], v[6:7], v[244:245], v[250:251] op_sel:[0,1,0] op_sel_hi:[1,1,1]
	s_waitcnt lgkmcnt(0)
	v_pk_fma_f32 v[250:251], v[12:13], v[246:247], v[250:251] op_sel:[0,0,0] op_sel_hi:[1,0,1]
	v_pk_fma_f32 v[250:251], v[8:9], v[246:247], v[250:251] op_sel:[0,1,0] op_sel_hi:[1,1,1]
	v_pk_fma_f32 v[250:251], v[4:5], v[248:249], v[250:251] op_sel:[0,0,0] op_sel_hi:[1,0,1]
	v_fma_f32 v119, v2, v249, v250
	v_fma_f32 v117, v3, v249, v251
	v_mul_f32_e64 v2, |v119|, s96
	v_exp_f32_e32 v2, v2
	v_mul_f32_e64 v3, |v117|, s96
	v_exp_f32_e32 v3, v3
	v_min_f32_e32 v4, 0, v119
	v_add_f32_e32 v2, 1.0, v2
	v_log_f32_e32 v2, v2
	v_add_f32_e32 v3, 1.0, v3
	v_log_f32_e32 v3, v3
	v_fmac_f32_e32 v4, 0xbf317218, v2
	v_min_f32_e32 v2, 0, v117
	v_fmac_f32_e32 v2, 0xbf317218, v3
	v_mul_f32_e32 v123, 0x3d800000, v4
	v_mul_f32_e32 v121, 0x3d800000, v2
	s_and_b64 vcc, exec, s[88:89]
	s_mov_b64 s[90:91], -1
	s_cbranch_vccnz .LBB0_346
; DI void phase_gla_prep(const Params& P, int l, int bid, int nb, LAS unsigned char* lds) {
;     ...
; #pragma unroll
;                 for (int r = 1; r < 8; ++r) { g0[r] += g0[r - 1]; g1[r] += g1[r - 1]; }
;                 float s0 = g0[7], s1 = g1[7];
; #pragma unroll
;                 for (int o = 8; o < 64; o <<= 1) { const float t0 = __shfl_up(s0, o), t1 = __shfl_up(s1, o); if (lane >= o) { s0 += t0; s1 += t1; } }
;                 const float e0 = s0 - g0[7], e1 = s1 - g1[7];
; #pragma unroll
;                 for (int r = 0; r < 8; ++r) { g0[r] += e0; g1[r] += e1; }
;                 tot0 = __shfl(s0, 56 + dpl); tot1 = __shfl(s1, 56 + dpl);
	v_add_f32_e32 v122, v233, v123
	v_add_f32_e32 v120, v232, v121
	v_add_f32_e32 v3, v231, v122
	v_add_f32_e32 v2, v229, v3
	v_add_f32_e32 v13, v230, v120
	v_add_f32_e32 v5, v227, v2
	v_add_f32_e32 v12, v228, v13
	v_add_f32_e32 v4, v225, v5
	v_add_f32_e32 v125, v226, v12
	v_add_f32_e32 v11, v221, v4
	v_add_f32_e32 v124, v224, v125
	v_add_f32_e32 v10, v118, v11
	v_add_f32_e32 v127, v222, v124
	ds_bpermute_b32 v6, v79, v10
	v_add_f32_e32 v126, v116, v127
	ds_bpermute_b32 v7, v79, v126
	s_mov_b64 s[90:91], 0
	s_waitcnt lgkmcnt(1)
	v_add_f32_e32 v6, v10, v6
	v_cndmask_b32_e64 v6, v10, v6, s[2:3]
	s_waitcnt lgkmcnt(0)
	v_add_f32_e32 v7, v126, v7
	ds_bpermute_b32 v8, v215, v6
	v_cndmask_b32_e64 v7, v126, v7, s[2:3]
	ds_bpermute_b32 v9, v215, v7
	s_waitcnt lgkmcnt(1)
	v_add_f32_e32 v8, v6, v8
	v_cndmask_b32_e64 v6, v6, v8, s[4:5]
	s_waitcnt lgkmcnt(0)
	v_add_f32_e32 v9, v7, v9
	ds_bpermute_b32 v8, v211, v6
	v_cndmask_b32_e64 v7, v7, v9, s[4:5]
	ds_bpermute_b32 v9, v211, v7
	s_waitcnt lgkmcnt(1)
	v_add_f32_e32 v8, v6, v8
	v_cndmask_b32_e64 v15, v6, v8, s[6:7]
	s_waitcnt lgkmcnt(0)
	v_add_f32_e32 v6, v7, v9
	v_cndmask_b32_e64 v117, v7, v6, s[6:7]
	v_sub_f32_e32 v128, v117, v126
	v_pk_add_f32 v[16:17], v[120:121], v[128:129] op_sel_hi:[1,0]
	ds_bpermute_b32 v119, v216, v15
	ds_bpermute_b32 v120, v216, v117
	v_sub_f32_e32 v14, v15, v10
	v_pk_add_f32 v[8:9], v[122:123], v[14:15] op_sel_hi:[1,0]
	v_pk_add_f32 v[6:7], v[2:3], v[14:15] op_sel_hi:[1,0]
	v_pk_add_f32 v[4:5], v[4:5], v[14:15] op_sel_hi:[1,0]
	v_pk_add_f32 v[2:3], v[10:11], v[14:15] op_sel_hi:[1,0]
	v_pk_add_f32 v[14:15], v[12:13], v[128:129] op_sel_hi:[1,0]
	v_pk_add_f32 v[12:13], v[124:125], v[128:129] op_sel_hi:[1,0]
	v_pk_add_f32 v[10:11], v[126:127], v[128:129] op_sel_hi:[1,0]

; #define LAS __attribute__((address_space(3)))
; DI float logsigmoid_fast(float z) { return fminf(z, 0.f) - 0.6931471805599453f * __builtin_amdgcn_logf(1.0f + __builtin_amdgcn_exp2f(-fabsf(z) * LOG2E)); }
; DI void phase_gla_prep(const Params& P, int l, int bid, int nb, LAS unsigned char* lds) {
;     ...
;         for (int dir = 0; dir < 2; ++dir) {
;             float w0[16], w1[16];
; #pragma unroll
;             for (int k = 0; k < 16; ++k) { const f32x2 t = *(const LAS f32x2*)(lds + PP_W + ((dir * 16 + k) * 128 + c0) * 4); w0[k] = t.x; w1[k] = t.y; }
;             const f32x2 bb = dir ? bbs[1] : bbs[0];
;             float g0[8], g1[8];
; #pragma unroll
;             for (int r = 0; r < 8; ++r) { float z0 = bb.x, z1 = bb.y; const LAS float* lr = (const LAS float*)(lds + PP_LR) + (rg * 8 + r) * 32 + dir * 16;
; #pragma unroll
;                 for (int k4 = 0; k4 < 4; ++k4) { const f32x4 t = *(const LAS f32x4*)(lr + k4 * 4);
; #pragma unroll
;                     for (int u = 0; u < 4; ++u) { z0 += t[u] * w0[k4 * 4 + u]; z1 += t[u] * w1[k4 * 4 + u]; } }
;                 g0[r] = logsigmoid_fast(z0) * 0.0625f; g1[r] = logsigmoid_fast(z1) * 0.0625f; __builtin_amdgcn_sched_barrier(0); }
.LBB0_906:
	s_lshl_b32 s64, s76, 13
	v_add_u32_e32 v2, s64, v142
	v_add_u32_e32 v3, s64, v143
	v_add_u32_e32 v4, s64, v144
	v_add_u32_e32 v5, s64, v145
	ds_read_b64 v[134:135], v2
	ds_read_b64 v[132:133], v3
	ds_read_b64 v[128:129], v4
	ds_read_b64 v[124:125], v5
	v_add_u32_e32 v2, s64, v147
	v_add_u32_e32 v3, s64, v148
	v_add_u32_e32 v4, s64, v149
	v_add_u32_e32 v5, s64, v150
	ds_read_b64 v[130:131], v2
	ds_read_b64 v[126:127], v3
	ds_read_b64 v[120:121], v4
	ds_read_b64 v[14:15], v5
	v_add_u32_e32 v2, s64, v151
	v_add_u32_e32 v3, s64, v152
	v_add_u32_e32 v4, s64, v153
	v_add_u32_e32 v5, s64, v154
	ds_read_b64 v[122:123], v2
	ds_read_b64 v[16:17], v3
	ds_read_b64 v[10:11], v4
	ds_read_b64 v[6:7], v5
	v_add_u32_e32 v2, s64, v155
	v_add_u32_e32 v3, s64, v156
	v_add_u32_e32 v4, s64, v157
	v_lshl_add_u32 v226, s76, 6, v178
	v_add_u32_e32 v116, s64, v158
	ds_read_b64 v[12:13], v2
	ds_read_b64 v[8:9], v3
	ds_read_b64 v[4:5], v4
	ds_read_b64 v[2:3], v116
	ds_read_b128 v[228:231], v226
	v_cndmask_b32_e64 v119, v82, v80, s[84:85]
	v_cndmask_b32_e64 v117, v83, v81, s[84:85]
	ds_read_b128 v[232:235], v226 offset:16
	ds_read_b128 v[236:239], v226 offset:32
	ds_read_b128 v[240:243], v226 offset:48
	s_waitcnt lgkmcnt(0)
	v_fma_f32 v244, v134, v228, v119
	v_fma_f32 v245, v135, v228, v117
	v_pk_fma_f32 v[244:245], v[132:133], v[228:229], v[244:245] op_sel:[0,1,0] op_sel_hi:[1,1,1]
	v_pk_fma_f32 v[244:245], v[128:129], v[230:231], v[244:245] op_sel:[0,0,0] op_sel_hi:[1,0,1]
	v_pk_fma_f32 v[244:245], v[124:125], v[230:231], v[244:245] op_sel:[0,1,0] op_sel_hi:[1,1,1]
	v_pk_fma_f32 v[244:245], v[130:131], v[232:233], v[244:245] op_sel:[0,0,0] op_sel_hi:[1,0,1]
	v_pk_fma_f32 v[244:245], v[126:127], v[232:233], v[244:245] op_sel:[0,1,0] op_sel_hi:[1,1,1]
	v_pk_fma_f32 v[244:245], v[120:121], v[234:235], v[244:245] op_sel:[0,0,0] op_sel_hi:[1,0,1]
	v_pk_fma_f32 v[244:245], v[14:15], v[234:235], v[244:245] op_sel:[0,1,0] op_sel_hi:[1,1,1]
	v_pk_fma_f32 v[244:245], v[122:123], v[236:237], v[244:245] op_sel:[0,0,0] op_sel_hi:[1,0,1]
	v_pk_fma_f32 v[244:245], v[16:17], v[236:237], v[244:245] op_sel:[0,1,0] op_sel_hi:[1,1,1]
	v_pk_fma_f32 v[244:245], v[10:11], v[238:239], v[244:245] op_sel:[0,0,0] op_sel_hi:[1,0,1]
	v_pk_fma_f32 v[244:245], v[6:7], v[238:239], v[244:245] op_sel:[0,1,0] op_sel_hi:[1,1,1]
	v_pk_fma_f32 v[244:245], v[12:13], v[240:241], v[244:245] op_sel:[0,0,0] op_sel_hi:[1,0,1]
	v_pk_fma_f32 v[244:245], v[8:9], v[240:241], v[244:245] op_sel:[0,1,0] op_sel_hi:[1,1,1]
	v_pk_fma_f32 v[244:245], v[4:5], v[242:243], v[244:245] op_sel:[0,0,0] op_sel_hi:[1,0,1]
	v_fma_f32 v116, v2, v243, v244
	v_fma_f32 v224, v3, v243, v245
	v_mul_f32_e64 v118, |v116|, s90
	v_exp_f32_e32 v118, v118
	v_mul_f32_e64 v225, |v224|, s90
	v_exp_f32_e32 v225, v225
	v_add_f32_e32 v118, 1.0, v118
	v_log_f32_e32 v118, v118
	v_min_f32_e32 v116, 0, v116
	v_add_f32_e32 v225, 1.0, v225
	v_log_f32_e32 v225, v225
	v_fmac_f32_e32 v116, 0xbf317218, v118
	v_mul_f32_e32 v118, 0x3d800000, v116
	v_min_f32_e32 v116, 0, v224
	v_fmac_f32_e32 v116, 0xbf317218, v225
	v_mul_f32_e32 v116, 0x3d800000, v116
	ds_read_b128 v[228:231], v226 offset:128
	ds_read_b128 v[232:235], v226 offset:144
	ds_read_b128 v[236:239], v226 offset:160
	ds_read_b128 v[240:243], v226 offset:176
	s_waitcnt lgkmcnt(3)
	v_fma_f32 v244, v134, v228, v119
	v_fma_f32 v245, v135, v228, v117
	v_pk_fma_f32 v[244:245], v[132:133], v[228:229], v[244:245] op_sel:[0,1,0] op_sel_hi:[1,1,1]
	v_pk_fma_f32 v[244:245], v[128:129], v[230:231], v[244:245] op_sel:[0,0,0] op_sel_hi:[1,0,1]
	v_pk_fma_f32 v[244:245], v[124:125], v[230:231], v[244:245] op_sel:[0,1,0] op_sel_hi:[1,1,1]
	s_waitcnt lgkmcnt(2)
	v_pk_fma_f32 v[244:245], v[130:131], v[232:233], v[244:245] op_sel:[0,0,0] op_sel_hi:[1,0,1]
	v_pk_fma_f32 v[244:245], v[126:127], v[232:233], v[244:245] op_sel:[0,1,0] op_sel_hi:[1,1,1]
	v_pk_fma_f32 v[244:245], v[120:121], v[234:235], v[244:245] op_sel:[0,0,0] op_sel_hi:[1,0,1]
	v_pk_fma_f32 v[244:245], v[14:15], v[234:235], v[244:245] op_sel:[0,1,0] op_sel_hi:[1,1,1]
	s_waitcnt lgkmcnt(1)
	v_pk_fma_f32 v[244:245], v[122:123], v[236:237], v[244:245] op_sel:[0,0,0] op_sel_hi:[1,0,1]
	v_pk_fma_f32 v[244:245], v[16:17], v[236:237], v[244:245] op_sel:[0,1,0] op_sel_hi:[1,1,1]
	v_pk_fma_f32 v[244:245], v[10:11], v[238:239], v[244:245] op_sel:[0,0,0] op_sel_hi:[1,0,1]
	v_pk_fma_f32 v[244:245], v[6:7], v[238:239], v[244:245] op_sel:[0,1,0] op_sel_hi:[1,1,1]
	s_waitcnt lgkmcnt(0)
	v_pk_fma_f32 v[244:245], v[12:13], v[240:241], v[244:245] op_sel:[0,0,0] op_sel_hi:[1,0,1]
	v_pk_fma_f32 v[244:245], v[8:9], v[240:241], v[244:245] op_sel:[0,1,0] op_sel_hi:[1,1,1]
	v_pk_fma_f32 v[244:245], v[4:5], v[242:243], v[244:245] op_sel:[0,0,0] op_sel_hi:[1,0,1]
	v_fma_f32 v224, v2, v243, v244
	v_fma_f32 v225, v3, v243, v245
	v_mul_f32_e64 v227, |v224|, s90
	v_mul_f32_e64 v228, |v225|, s90
	v_exp_f32_e32 v227, v227
	v_exp_f32_e32 v228, v228
	v_min_f32_e32 v224, 0, v224
	v_min_f32_e32 v225, 0, v225
	v_add_f32_e32 v227, 1.0, v227
	v_add_f32_e32 v228, 1.0, v228
	v_log_f32_e32 v227, v227
	v_log_f32_e32 v228, v228
	v_fmac_f32_e32 v224, 0xbf317218, v227
	v_fmac_f32_e32 v225, 0xbf317218, v228
	v_mul_f32_e32 v224, 0x3d800000, v224
	v_mul_f32_e32 v225, 0x3d800000, v225
	ds_read_b128 v[228:231], v226 offset:256
	ds_read_b128 v[232:235], v226 offset:272
	ds_read_b128 v[236:239], v226 offset:288
	ds_read_b128 v[240:243], v226 offset:304
	s_waitcnt lgkmcnt(3)
	v_fma_f32 v246, v134, v228, v119
	v_fma_f32 v247, v135, v228, v117
	v_pk_fma_f32 v[246:247], v[132:133], v[228:229], v[246:247] op_sel:[0,1,0] op_sel_hi:[1,1,1]
	v_pk_fma_f32 v[246:247], v[128:129], v[230:231], v[246:247] op_sel:[0,0,0] op_sel_hi:[1,0,1]
	v_pk_fma_f32 v[246:247], v[124:125], v[230:231], v[246:247] op_sel:[0,1,0] op_sel_hi:[1,1,1]
	s_waitcnt lgkmcnt(2)
; #define LAS __attribute__((address_space(3)))
; DI float logsigmoid_fast(float z) { return fminf(z, 0.f) - 0.6931471805599453f * __builtin_amdgcn_logf(1.0f + __builtin_amdgcn_exp2f(-fabsf(z) * LOG2E)); }
; DI void phase_gla_prep(const Params& P, int l, int bid, int nb, LAS unsigned char* lds) {
;     ...
;             for (int r = 0; r < 8; ++r) { float z0 = bb.x, z1 = bb.y; const LAS float* lr = (const LAS float*)(lds + PP_LR) + (rg * 8 + r) * 32 + dir * 16;
; #pragma unroll
;                 for (int k4 = 0; k4 < 4; ++k4) { const f32x4 t = *(const LAS f32x4*)(lr + k4 * 4);
; #pragma unroll
;                     for (int u = 0; u < 4; ++u) { z0 += t[u] * w0[k4 * 4 + u]; z1 += t[u] * w1[k4 * 4 + u]; } }
;                 g0[r] = logsigmoid_fast(z0) * 0.0625f; g1[r] = logsigmoid_fast(z1) * 0.0625f; __builtin_amdgcn_sched_barrier(0); }
	v_pk_fma_f32 v[246:247], v[130:131], v[232:233], v[246:247] op_sel:[0,0,0] op_sel_hi:[1,0,1]
	v_pk_fma_f32 v[246:247], v[126:127], v[232:233], v[246:247] op_sel:[0,1,0] op_sel_hi:[1,1,1]
	v_pk_fma_f32 v[246:247], v[120:121], v[234:235], v[246:247] op_sel:[0,0,0] op_sel_hi:[1,0,1]
	v_pk_fma_f32 v[246:247], v[14:15], v[234:235], v[246:247] op_sel:[0,1,0] op_sel_hi:[1,1,1]
	s_waitcnt lgkmcnt(1)
	v_pk_fma_f32 v[246:247], v[122:123], v[236:237], v[246:247] op_sel:[0,0,0] op_sel_hi:[1,0,1]
	v_pk_fma_f32 v[246:247], v[16:17], v[236:237], v[246:247] op_sel:[0,1,0] op_sel_hi:[1,1,1]
	v_pk_fma_f32 v[246:247], v[10:11], v[238:239], v[246:247] op_sel:[0,0,0] op_sel_hi:[1,0,1]
	v_pk_fma_f32 v[246:247], v[6:7], v[238:239], v[246:247] op_sel:[0,1,0] op_sel_hi:[1,1,1]
	s_waitcnt lgkmcnt(0)
	v_pk_fma_f32 v[246:247], v[12:13], v[240:241], v[246:247] op_sel:[0,0,0] op_sel_hi:[1,0,1]
	v_pk_fma_f32 v[246:247], v[8:9], v[240:241], v[246:247] op_sel:[0,1,0] op_sel_hi:[1,1,1]
	v_pk_fma_f32 v[246:247], v[4:5], v[242:243], v[246:247] op_sel:[0,0,0] op_sel_hi:[1,0,1]
	v_fma_f32 v227, v2, v243, v246
	v_fma_f32 v244, v3, v243, v247
	v_mul_f32_e64 v228, |v227|, s90
	v_exp_f32_e32 v228, v228
	v_mul_f32_e64 v229, |v244|, s90
	v_exp_f32_e32 v229, v229
	v_add_f32_e32 v228, 1.0, v228
	v_log_f32_e32 v228, v228
	v_min_f32_e32 v227, 0, v227
	v_add_f32_e32 v229, 1.0, v229
	v_log_f32_e32 v229, v229
	v_fmac_f32_e32 v227, 0xbf317218, v228
	v_mul_f32_e32 v228, 0x3d800000, v227
	v_min_f32_e32 v227, 0, v244
	v_fmac_f32_e32 v227, 0xbf317218, v229
	v_mul_f32_e32 v227, 0x3d800000, v227
	ds_read_b128 v[230:233], v226 offset:384
	ds_read_b128 v[234:237], v226 offset:400
	ds_read_b128 v[238:241], v226 offset:416
	ds_read_b128 v[242:245], v226 offset:432
	s_waitcnt lgkmcnt(3)
	v_fma_f32 v248, v134, v230, v119
	v_fma_f32 v249, v135, v230, v117
	v_pk_fma_f32 v[248:249], v[132:133], v[230:231], v[248:249] op_sel:[0,1,0] op_sel_hi:[1,1,1]
	v_pk_fma_f32 v[248:249], v[128:129], v[232:233], v[248:249] op_sel:[0,0,0] op_sel_hi:[1,0,1]
	v_pk_fma_f32 v[248:249], v[124:125], v[232:233], v[248:249] op_sel:[0,1,0] op_sel_hi:[1,1,1]
	s_waitcnt lgkmcnt(2)
	v_pk_fma_f32 v[248:249], v[130:131], v[234:235], v[248:249] op_sel:[0,0,0] op_sel_hi:[1,0,1]
	v_pk_fma_f32 v[248:249], v[126:127], v[234:235], v[248:249] op_sel:[0,1,0] op_sel_hi:[1,1,1]
	v_pk_fma_f32 v[248:249], v[120:121], v[236:237], v[248:249] op_sel:[0,0,0] op_sel_hi:[1,0,1]
	v_pk_fma_f32 v[248:249], v[14:15], v[236:237], v[248:249] op_sel:[0,1,0] op_sel_hi:[1,1,1]
	s_waitcnt lgkmcnt(1)
	v_pk_fma_f32 v[248:249], v[122:123], v[238:239], v[248:249] op_sel:[0,0,0] op_sel_hi:[1,0,1]
	v_pk_fma_f32 v[248:249], v[16:17], v[238:239], v[248:249] op_sel:[0,1,0] op_sel_hi:[1,1,1]
	v_pk_fma_f32 v[248:249], v[10:11], v[240:241], v[248:249] op_sel:[0,0,0] op_sel_hi:[1,0,1]
	v_pk_fma_f32 v[248:249], v[6:7], v[240:241], v[248:249] op_sel:[0,1,0] op_sel_hi:[1,1,1]
	s_waitcnt lgkmcnt(0)
	v_pk_fma_f32 v[248:249], v[12:13], v[242:243], v[248:249] op_sel:[0,0,0] op_sel_hi:[1,0,1]
	v_pk_fma_f32 v[248:249], v[8:9], v[242:243], v[248:249] op_sel:[0,1,0] op_sel_hi:[1,1,1]
	v_pk_fma_f32 v[248:249], v[4:5], v[244:245], v[248:249] op_sel:[0,0,0] op_sel_hi:[1,0,1]
	v_fma_f32 v229, v2, v245, v248
	v_fma_f32 v246, v3, v245, v249
	v_mul_f32_e64 v230, |v229|, s90
	v_exp_f32_e32 v230, v230
	v_mul_f32_e64 v231, |v246|, s90
	v_exp_f32_e32 v231, v231
	v_add_f32_e32 v230, 1.0, v230
	v_log_f32_e32 v230, v230
	v_min_f32_e32 v229, 0, v229
	v_add_f32_e32 v231, 1.0, v231
	v_log_f32_e32 v231, v231
	v_fmac_f32_e32 v229, 0xbf317218, v230
	v_mul_f32_e32 v230, 0x3d800000, v229
	v_min_f32_e32 v229, 0, v246
	v_fmac_f32_e32 v229, 0xbf317218, v231
	v_mul_f32_e32 v229, 0x3d800000, v229
	ds_read_b128 v[232:235], v226 offset:512
	ds_read_b128 v[236:239], v226 offset:528
	ds_read_b128 v[240:243], v226 offset:544
	ds_read_b128 v[244:247], v226 offset:560
	s_waitcnt lgkmcnt(3)
	v_fma_f32 v250, v134, v232, v119
	v_fma_f32 v251, v135, v232, v117
	v_pk_fma_f32 v[250:251], v[132:133], v[232:233], v[250:251] op_sel:[0,1,0] op_sel_hi:[1,1,1]
	v_pk_fma_f32 v[250:251], v[128:129], v[234:235], v[250:251] op_sel:[0,0,0] op_sel_hi:[1,0,1]
	v_pk_fma_f32 v[250:251], v[124:125], v[234:235], v[250:251] op_sel:[0,1,0] op_sel_hi:[1,1,1]
	s_waitcnt lgkmcnt(2)
	v_pk_fma_f32 v[250:251], v[130:131], v[236:237], v[250:251] op_sel:[0,0,0] op_sel_hi:[1,0,1]
	v_pk_fma_f32 v[250:251], v[126:127], v[236:237], v[250:251] op_sel:[0,1,0] op_sel_hi:[1,1,1]
	v_pk_fma_f32 v[250:251], v[120:121], v[238:239], v[250:251] op_sel:[0,0,0] op_sel_hi:[1,0,1]
	v_pk_fma_f32 v[250:251], v[14:15], v[238:239], v[250:251] op_sel:[0,1,0] op_sel_hi:[1,1,1]
	s_waitcnt lgkmcnt(1)
	v_pk_fma_f32 v[250:251], v[122:123], v[240:241], v[250:251] op_sel:[0,0,0] op_sel_hi:[1,0,1]
	v_pk_fma_f32 v[250:251], v[16:17], v[240:241], v[250:251] op_sel:[0,1,0] op_sel_hi:[1,1,1]
	v_pk_fma_f32 v[250:251], v[10:11], v[242:243], v[250:251] op_sel:[0,0,0] op_sel_hi:[1,0,1]
	v_pk_fma_f32 v[250:251], v[6:7], v[242:243], v[250:251] op_sel:[0,1,0] op_sel_hi:[1,1,1]
	s_waitcnt lgkmcnt(0)
	v_pk_fma_f32 v[250:251], v[12:13], v[244:245], v[250:251] op_sel:[0,0,0] op_sel_hi:[1,0,1]
	v_pk_fma_f32 v[250:251], v[8:9], v[244:245], v[250:251] op_sel:[0,1,0] op_sel_hi:[1,1,1]
	v_pk_fma_f32 v[250:251], v[4:5], v[246:247], v[250:251] op_sel:[0,0,0] op_sel_hi:[1,0,1]
	v_fma_f32 v231, v2, v247, v250
	v_fma_f32 v248, v3, v247, v251
	v_mul_f32_e64 v232, |v231|, s90
	v_exp_f32_e32 v232, v232
	v_mul_f32_e64 v233, |v248|, s90
	v_exp_f32_e32 v233, v233
	v_add_f32_e32 v232, 1.0, v232
	v_log_f32_e32 v232, v232
	v_min_f32_e32 v231, 0, v231
	v_add_f32_e32 v233, 1.0, v233
	v_log_f32_e32 v233, v233
	v_fmac_f32_e32 v231, 0xbf317218, v232
	v_mul_f32_e32 v232, 0x3d800000, v231
	v_min_f32_e32 v231, 0, v248
	v_fmac_f32_e32 v231, 0xbf317218, v233
	v_mul_f32_e32 v231, 0x3d800000, v231
	ds_read_b128 v[234:237], v226 offset:640
	ds_read_b128 v[238:241], v226 offset:656
	ds_read_b128 v[242:245], v226 offset:672
	ds_read_b128 v[246:249], v226 offset:688
	s_waitcnt lgkmcnt(3)
; #define LAS __attribute__((address_space(3)))
; DI float logsigmoid_fast(float z) { return fminf(z, 0.f) - 0.6931471805599453f * __builtin_amdgcn_logf(1.0f + __builtin_amdgcn_exp2f(-fabsf(z) * LOG2E)); }
; DI void phase_gla_prep(const Params& P, int l, int bid, int nb, LAS unsigned char* lds) {
;     ...
;             for (int r = 0; r < 8; ++r) { float z0 = bb.x, z1 = bb.y; const LAS float* lr = (const LAS float*)(lds + PP_LR) + (rg * 8 + r) * 32 + dir * 16;
; #pragma unroll
;                 for (int k4 = 0; k4 < 4; ++k4) { const f32x4 t = *(const LAS f32x4*)(lr + k4 * 4);
; #pragma unroll
;                     for (int u = 0; u < 4; ++u) { z0 += t[u] * w0[k4 * 4 + u]; z1 += t[u] * w1[k4 * 4 + u]; } }
;                 g0[r] = logsigmoid_fast(z0) * 0.0625f; g1[r] = logsigmoid_fast(z1) * 0.0625f; __builtin_amdgcn_sched_barrier(0); }
	v_fma_f32 v252, v134, v234, v119
	v_fma_f32 v253, v135, v234, v117
	v_pk_fma_f32 v[252:253], v[132:133], v[234:235], v[252:253] op_sel:[0,1,0] op_sel_hi:[1,1,1]
	v_pk_fma_f32 v[252:253], v[128:129], v[236:237], v[252:253] op_sel:[0,0,0] op_sel_hi:[1,0,1]
	v_pk_fma_f32 v[252:253], v[124:125], v[236:237], v[252:253] op_sel:[0,1,0] op_sel_hi:[1,1,1]
	s_waitcnt lgkmcnt(2)
	v_pk_fma_f32 v[252:253], v[130:131], v[238:239], v[252:253] op_sel:[0,0,0] op_sel_hi:[1,0,1]
	v_pk_fma_f32 v[252:253], v[126:127], v[238:239], v[252:253] op_sel:[0,1,0] op_sel_hi:[1,1,1]
	v_pk_fma_f32 v[252:253], v[120:121], v[240:241], v[252:253] op_sel:[0,0,0] op_sel_hi:[1,0,1]
	v_pk_fma_f32 v[252:253], v[14:15], v[240:241], v[252:253] op_sel:[0,1,0] op_sel_hi:[1,1,1]
	s_waitcnt lgkmcnt(1)
	v_pk_fma_f32 v[252:253], v[122:123], v[242:243], v[252:253] op_sel:[0,0,0] op_sel_hi:[1,0,1]
	v_pk_fma_f32 v[252:253], v[16:17], v[242:243], v[252:253] op_sel:[0,1,0] op_sel_hi:[1,1,1]
	v_pk_fma_f32 v[252:253], v[10:11], v[244:245], v[252:253] op_sel:[0,0,0] op_sel_hi:[1,0,1]
	v_pk_fma_f32 v[252:253], v[6:7], v[244:245], v[252:253] op_sel:[0,1,0] op_sel_hi:[1,1,1]
	s_waitcnt lgkmcnt(0)
	v_pk_fma_f32 v[252:253], v[12:13], v[246:247], v[252:253] op_sel:[0,0,0] op_sel_hi:[1,0,1]
	v_pk_fma_f32 v[252:253], v[8:9], v[246:247], v[252:253] op_sel:[0,1,0] op_sel_hi:[1,1,1]
	v_pk_fma_f32 v[252:253], v[4:5], v[248:249], v[252:253] op_sel:[0,0,0] op_sel_hi:[1,0,1]
	v_fma_f32 v233, v2, v249, v252
	v_fma_f32 v250, v3, v249, v253
	v_mul_f32_e64 v234, |v233|, s90
	v_exp_f32_e32 v234, v234
	v_mul_f32_e64 v235, |v250|, s90
	v_exp_f32_e32 v235, v235
	v_add_f32_e32 v234, 1.0, v234
	v_log_f32_e32 v234, v234
	v_min_f32_e32 v233, 0, v233
	v_add_f32_e32 v235, 1.0, v235
	v_log_f32_e32 v235, v235
	v_fmac_f32_e32 v233, 0xbf317218, v234
	v_mul_f32_e32 v234, 0x3d800000, v233
	v_min_f32_e32 v233, 0, v250
	v_fmac_f32_e32 v233, 0xbf317218, v235
	v_mul_f32_e32 v233, 0x3d800000, v233
	ds_read_b128 v[236:239], v226 offset:768
	ds_read_b128 v[240:243], v226 offset:784
	ds_read_b128 v[244:247], v226 offset:800
	ds_read_b128 v[248:251], v226 offset:816
	s_waitcnt lgkmcnt(3)
	v_fma_f32 v235, v134, v236, v119
	v_fma_f32 v252, v135, v236, v117
	v_fma_f32 v236, v132, v237, v235
	v_fma_f32 v237, v133, v237, v252
	v_pk_fma_f32 v[236:237], v[128:129], v[238:239], v[236:237] op_sel:[0,0,0] op_sel_hi:[1,0,1]
	v_pk_fma_f32 v[236:237], v[124:125], v[238:239], v[236:237] op_sel:[0,1,0] op_sel_hi:[1,1,1]
	s_waitcnt lgkmcnt(2)
	v_pk_fma_f32 v[236:237], v[130:131], v[240:241], v[236:237] op_sel:[0,0,0] op_sel_hi:[1,0,1]
	v_pk_fma_f32 v[236:237], v[126:127], v[240:241], v[236:237] op_sel:[0,1,0] op_sel_hi:[1,1,1]
	v_pk_fma_f32 v[236:237], v[120:121], v[242:243], v[236:237] op_sel:[0,0,0] op_sel_hi:[1,0,1]
	v_pk_fma_f32 v[236:237], v[14:15], v[242:243], v[236:237] op_sel:[0,1,0] op_sel_hi:[1,1,1]
	s_waitcnt lgkmcnt(1)
	v_pk_fma_f32 v[236:237], v[122:123], v[244:245], v[236:237] op_sel:[0,0,0] op_sel_hi:[1,0,1]
	v_pk_fma_f32 v[236:237], v[16:17], v[244:245], v[236:237] op_sel:[0,1,0] op_sel_hi:[1,1,1]
	v_pk_fma_f32 v[236:237], v[10:11], v[246:247], v[236:237] op_sel:[0,0,0] op_sel_hi:[1,0,1]
	v_pk_fma_f32 v[236:237], v[6:7], v[246:247], v[236:237] op_sel:[0,1,0] op_sel_hi:[1,1,1]
	s_waitcnt lgkmcnt(0)
	v_pk_fma_f32 v[236:237], v[12:13], v[248:249], v[236:237] op_sel:[0,0,0] op_sel_hi:[1,0,1]
	v_pk_fma_f32 v[236:237], v[8:9], v[248:249], v[236:237] op_sel:[0,1,0] op_sel_hi:[1,1,1]
	v_pk_fma_f32 v[236:237], v[4:5], v[250:251], v[236:237] op_sel:[0,0,0] op_sel_hi:[1,0,1]
	v_fma_f32 v235, v2, v251, v236
	v_fma_f32 v252, v3, v251, v237
	v_mul_f32_e64 v236, |v235|, s90
	v_exp_f32_e32 v236, v236
	v_mul_f32_e64 v237, |v252|, s90
	v_exp_f32_e32 v237, v237
	v_add_f32_e32 v236, 1.0, v236
	v_log_f32_e32 v236, v236
	v_min_f32_e32 v235, 0, v235
	v_add_f32_e32 v237, 1.0, v237
	v_log_f32_e32 v237, v237
	v_fmac_f32_e32 v235, 0xbf317218, v236
	v_mul_f32_e32 v236, 0x3d800000, v235
	v_min_f32_e32 v235, 0, v252
	v_fmac_f32_e32 v235, 0xbf317218, v237
	v_mul_f32_e32 v235, 0x3d800000, v235
	ds_read_b128 v[238:241], v226 offset:896
	ds_read_b128 v[242:245], v226 offset:912
	ds_read_b128 v[246:249], v226 offset:928
	ds_read_b128 v[250:253], v226 offset:944
	s_waitcnt lgkmcnt(3)
	v_fmac_f32_e32 v119, v134, v238
	v_fmac_f32_e32 v117, v135, v238
	v_fma_f32 v238, v132, v239, v119
	v_fma_f32 v239, v133, v239, v117
	v_pk_fma_f32 v[238:239], v[128:129], v[240:241], v[238:239] op_sel:[0,0,0] op_sel_hi:[1,0,1]
	v_pk_fma_f32 v[238:239], v[124:125], v[240:241], v[238:239] op_sel:[0,1,0] op_sel_hi:[1,1,1]
	s_waitcnt lgkmcnt(2)
	v_pk_fma_f32 v[238:239], v[130:131], v[242:243], v[238:239] op_sel:[0,0,0] op_sel_hi:[1,0,1]
	v_pk_fma_f32 v[238:239], v[126:127], v[242:243], v[238:239] op_sel:[0,1,0] op_sel_hi:[1,1,1]
	v_pk_fma_f32 v[238:239], v[120:121], v[244:245], v[238:239] op_sel:[0,0,0] op_sel_hi:[1,0,1]
	v_pk_fma_f32 v[238:239], v[14:15], v[244:245], v[238:239] op_sel:[0,1,0] op_sel_hi:[1,1,1]
	s_waitcnt lgkmcnt(1)
	v_pk_fma_f32 v[238:239], v[122:123], v[246:247], v[238:239] op_sel:[0,0,0] op_sel_hi:[1,0,1]
	v_pk_fma_f32 v[238:239], v[16:17], v[246:247], v[238:239] op_sel:[0,1,0] op_sel_hi:[1,1,1]
	v_pk_fma_f32 v[238:239], v[10:11], v[248:249], v[238:239] op_sel:[0,0,0] op_sel_hi:[1,0,1]
	v_pk_fma_f32 v[238:239], v[6:7], v[248:249], v[238:239] op_sel:[0,1,0] op_sel_hi:[1,1,1]
	s_waitcnt lgkmcnt(0)
	v_pk_fma_f32 v[238:239], v[12:13], v[250:251], v[238:239] op_sel:[0,0,0] op_sel_hi:[1,0,1]
	v_pk_fma_f32 v[238:239], v[8:9], v[250:251], v[238:239] op_sel:[0,1,0] op_sel_hi:[1,1,1]
	v_pk_fma_f32 v[238:239], v[4:5], v[252:253], v[238:239] op_sel:[0,0,0] op_sel_hi:[1,0,1]
	v_fma_f32 v119, v2, v253, v238
	v_fma_f32 v117, v3, v253, v239
	v_mul_f32_e64 v2, |v119|, s90
	v_exp_f32_e32 v2, v2
	v_mul_f32_e64 v3, |v117|, s90
	v_exp_f32_e32 v3, v3
	v_min_f32_e32 v4, 0, v119
	v_add_f32_e32 v2, 1.0, v2
	v_log_f32_e32 v2, v2
	v_add_f32_e32 v3, 1.0, v3
	v_log_f32_e32 v3, v3
	v_fmac_f32_e32 v4, 0xbf317218, v2
	v_min_f32_e32 v2, 0, v117
	v_fmac_f32_e32 v2, 0xbf317218, v3
	v_mul_f32_e32 v123, 0x3d800000, v4
	v_mul_f32_e32 v121, 0x3d800000, v2
	s_and_b64 vcc, exec, s[84:85]
	s_mov_b64 s[86:87], -1
	s_cbranch_vccnz .LBB0_908
; DI void phase_gla_prep(const Params& P, int l, int bid, int nb, LAS unsigned char* lds) {
;     ...
; #pragma unroll
;                 for (int r = 1; r < 8; ++r) { g0[r] += g0[r - 1]; g1[r] += g1[r - 1]; }
;                 float s0 = g0[7], s1 = g1[7];
; #pragma unroll
;                 for (int o = 8; o < 64; o <<= 1) { const float t0 = __shfl_up(s0, o), t1 = __shfl_up(s1, o); if (lane >= o) { s0 += t0; s1 += t1; } }
;                 const float e0 = s0 - g0[7], e1 = s1 - g1[7];
; #pragma unroll
;                 for (int r = 0; r < 8; ++r) { g0[r] += e0; g1[r] += e1; }
;                 tot0 = __shfl(s0, 56 + dpl); tot1 = __shfl(s1, 56 + dpl);
	v_add_f32_e32 v122, v236, v123
	v_add_f32_e32 v120, v235, v121
	v_add_f32_e32 v3, v234, v122
	v_add_f32_e32 v2, v232, v3
	v_add_f32_e32 v13, v233, v120
	v_add_f32_e32 v5, v230, v2
	v_add_f32_e32 v12, v231, v13
	v_add_f32_e32 v4, v228, v5
	v_add_f32_e32 v125, v229, v12
	v_add_f32_e32 v11, v224, v4
	v_add_f32_e32 v124, v227, v125
	v_add_f32_e32 v10, v118, v11
	v_add_f32_e32 v127, v225, v124
	ds_bpermute_b32 v6, v79, v10
	v_add_f32_e32 v126, v116, v127
	ds_bpermute_b32 v7, v79, v126
	s_mov_b64 s[86:87], 0
	s_waitcnt lgkmcnt(1)
	v_add_f32_e32 v6, v10, v6
	v_cndmask_b32_e64 v6, v10, v6, s[2:3]
	s_waitcnt lgkmcnt(0)
	v_add_f32_e32 v7, v126, v7
	ds_bpermute_b32 v8, v218, v6
	v_cndmask_b32_e64 v7, v126, v7, s[2:3]
	ds_bpermute_b32 v9, v218, v7
	s_waitcnt lgkmcnt(1)
	v_add_f32_e32 v8, v6, v8
	v_cndmask_b32_e64 v6, v6, v8, s[4:5]
	s_waitcnt lgkmcnt(0)
	v_add_f32_e32 v9, v7, v9
	ds_bpermute_b32 v8, v214, v6
	v_cndmask_b32_e64 v7, v7, v9, s[4:5]
	ds_bpermute_b32 v9, v214, v7
	s_waitcnt lgkmcnt(1)
	v_add_f32_e32 v8, v6, v8
	v_cndmask_b32_e64 v15, v6, v8, s[6:7]
	s_waitcnt lgkmcnt(0)
	v_add_f32_e32 v6, v7, v9
	v_cndmask_b32_e64 v117, v7, v6, s[6:7]
	v_sub_f32_e32 v128, v117, v126
	v_pk_add_f32 v[16:17], v[120:121], v[128:129] op_sel_hi:[1,0]
	ds_bpermute_b32 v119, v219, v15
	ds_bpermute_b32 v120, v219, v117
	v_sub_f32_e32 v14, v15, v10
	v_pk_add_f32 v[8:9], v[122:123], v[14:15] op_sel_hi:[1,0]
	v_pk_add_f32 v[6:7], v[2:3], v[14:15] op_sel_hi:[1,0]
	v_pk_add_f32 v[4:5], v[4:5], v[14:15] op_sel_hi:[1,0]
	v_pk_add_f32 v[2:3], v[10:11], v[14:15] op_sel_hi:[1,0]
	v_pk_add_f32 v[14:15], v[12:13], v[128:129] op_sel_hi:[1,0]
	v_pk_add_f32 v[12:13], v[124:125], v[128:129] op_sel_hi:[1,0]
	v_pk_add_f32 v[10:11], v[126:127], v[128:129] op_sel_hi:[1,0]
